# hg_passB: stage Q'/o_local/gate tiles via coalesced XOR-swizzled LDS-DMA + ds_read fragments (ch!=0 fast path) instead of 48 row-scattered loads per lane
# speedup vs baseline: 1.0229x; 1.0105x over previous
; __global__ void __launch_bounds__(512, 2) fwd_megakernel(Ptrs Parg) {
;     ...
;           while (it < 24 * NCH) { const int t2 = pg8::wg_tid(glds);
;               if (t2 == 0) nxt = atomicAdd(qctr, 1u);
;               if (it < 8 * NCH) { const int ch = it % NCH, bg = it / NCH; ssd_passB(P, l, bg >> 2, ch, bg & 3, lds, t2, true); }
;               else { const int i2 = it - 8 * NCH; const int ch = i2 % NCH, bh = i2 / NCH; hg_passB(P, l, bh >> 3, bh & 7, ch, lds, t2, true); }
.LBB0_773:
	s_add_i32 s4, s10, 0xfbf8
	s_and_b32 s3, s4, 0xffff
	s_mul_i32 s5, s3, 0x3f81
	s_lshr_b32 s3, s5, 21
	s_mul_i32 s9, s3, 0x81
	s_sub_i32 s4, s4, s9
	s_and_b32 s11, s4, 0xffff
	s_lshr_b32 s13, s5, 24
	s_cmp_lg_u32 s11, 0
	s_cselect_b64 s[4:5], -1, 0
	s_and_b64 vcc, exec, s[4:5]
	s_cbranch_vccz .LBB0_790
	s_branch .Lhpb_fast
	s_lshl_b32 s6, s13, 14
	s_lshl_b32 s7, s11, 7
	s_add_i32 s6, s7, s6
	s_add_i32 s8, s6, 0xffffff80
	s_cbranch_execnz .LBB0_776

; __device__ __forceinline__ void hg_passB(const Ptrs& P, int l, int b, int hd, int ch, unsigned char* lds, int tid, bool dost) {
;     ...
;     const int lane = tid & 63, w = tid >> 6, lc = lane & 15, g = lane >> 4;
;     const int nsub = (ch == 0) ? 1 : 8;
;     const size_t row0 = (ch == 0) ? (size_t)(MMAIN + b * NMETA) : (size_t)(b * SEQ + 128 * (ch - 1));
.Lhpb_fast:
	s_lshl_b32 s6, s13, 14
	s_lshl_b32 s7, s11, 7
	s_add_i32 s6, s7, s6
	s_add_i32 s8, s6, 0xffffff80
	s_cbranch_execnz .Lhpb_776

; __device__ __forceinline__ void hg_passB(const Ptrs& P, int l, int b, int hd, int ch, unsigned char* lds, int tid, bool dost) {
;     ...
;     bf16x8 sfr[4];
; #pragma unroll
;     for (int ks = 0; ks < 4; ++ks) sfr[ks] = *(const bf16x8*)(HS + (16 * w + lc) * 128 + 32 * ks + 8 * g);
;     u32x2 ol[8], gv_[8];
; #pragma unroll
;     for (int j = 0; j < 8; ++j) { ol[j] = (u32x2){0u, 0u}; gv_[j] = ol[j];
;         if (j < nsub) { const bf16_t* rp = PJ + (row0 + 16 * j + lc) * PW + hd * 128 + 16 * w + 4 * g; ol[j] = *(const u32x2*)(rp + C_HI); gv_[j] = *(const u32x2*)(rp + C_HG); } }
.Lhpb_776:
	s_mov_b32 s15, s8
	s_add_i32 s9, s9, s11
	s_lshl_b32 s3, s3, 7
	v_ashrrev_i32_e32 v212, 6, v211
	s_lshl_b32 s96, s9, 15
	s_and_b32 s3, s3, 0x380
	v_and_b32_e32 v17, 15, v211
	v_lshl_add_u64 v[8:9], v[162:163], 0, s[96:97]
	s_lshl_b32 s96, s3, 1
	v_lshlrev_b32_e32 v188, 4, v212
	v_bfe_u32 v195, v211, 4, 2
	v_lshlrev_b32_e32 v10, 7, v17
	v_lshl_add_u64 v[20:21], v[160:161], 0, s[96:97]
	v_ashrrev_i32_e32 v189, 31, v188
	v_lshl_or_b32 v10, v212, 11, v10
	v_lshlrev_b32_e32 v18, 3, v195
	v_mov_b32_e32 v19, v16
	v_lshl_add_u64 v[20:21], v[188:189], 1, v[20:21]
	v_ashrrev_i32_e32 v11, 31, v10
	v_add_u32_e32 v22, s8, v17
	v_lshl_add_u64 v[20:21], v[20:21], 0, v[18:19]
	v_lshl_add_u64 v[8:9], v[10:11], 1, v[8:9]
	v_and_b32_e32 v10, 48, v211
	v_mov_b32_e32 v11, v16
	v_mad_u64_u32 v[20:21], s[6:7], v22, s34, v[20:21]
	v_lshl_add_u64 v[8:9], v[8:9], 0, v[10:11]
	v_add_co_u32_e32 v24, vcc, 0x3000, v20
	global_load_dwordx4 v[34:37], v[8:9], off
	global_load_dwordx4 v[30:33], v[8:9], off offset:64
	global_load_dwordx4 v[12:15], v[8:9], off offset:128
	s_nop 0
	global_load_dwordx4 v[8:11], v[8:9], off offset:192
	v_addc_co_u32_e32 v25, vcc, 0, v21, vcc
	v_add_co_u32_e32 v26, vcc, 0x1000, v20
	v_cndmask_b32_e64 v19, 0, 1, s[4:5]
	s_nop 0
	v_addc_co_u32_e32 v27, vcc, 0, v21, vcc
	v_mov_b32_e32 v196, 0
	v_cmp_ne_u32_e64 s[38:39], 1, v19
	s_andn2_b64 vcc, exec, s[4:5]
	v_mov_b32_e32 v198, 0
	v_mov_b32_e32 v199, 0
	v_mov_b32_e32 v186, 0
	v_mov_b32_e32 v187, 0
	s_cbranch_vccnz .Lhpb_778
	v_add_co_u32_e32 v24, vcc, 0x45000, v20
	s_nop 1
	v_addc_co_u32_e32 v25, vcc, 0, v21, vcc
	v_add_co_u32_e32 v26, vcc, 0x43000, v20
	s_nop 1
	v_addc_co_u32_e32 v27, vcc, 0, v21, vcc
.Lhpb_778:
	s_and_b64 vcc, exec, s[38:39]
	v_mov_b32_e32 v197, 0
	v_mov_b32_e32 v184, 0
	v_mov_b32_e32 v185, 0
	s_cbranch_vccnz .Lhpb_780
	v_add_co_u32_e32 v24, vcc, 0x87000, v20
	s_nop 1
	v_addc_co_u32_e32 v25, vcc, 0, v21, vcc
	v_add_co_u32_e32 v26, vcc, 0x85000, v20
	s_nop 1
	v_addc_co_u32_e32 v27, vcc, 0, v21, vcc
.Lhpb_780:
	v_mov_b32_e32 v200, 0
	s_and_b64 vcc, exec, s[38:39]
	v_mov_b32_e32 v202, 0
	v_mov_b32_e32 v203, 0
	v_mov_b32_e32 v182, 0
	v_mov_b32_e32 v183, 0
	s_cbranch_vccnz .Lhpb_782
	v_add_co_u32_e32 v24, vcc, 0xc9000, v20
	s_nop 1
	v_addc_co_u32_e32 v25, vcc, 0, v21, vcc
	v_add_co_u32_e32 v26, vcc, 0xc7000, v20
	s_nop 1
	v_addc_co_u32_e32 v27, vcc, 0, v21, vcc
.Lhpb_782:
	s_and_b64 vcc, exec, s[38:39]
	v_mov_b32_e32 v201, 0
	v_mov_b32_e32 v180, 0
	v_mov_b32_e32 v181, 0
	s_cbranch_vccnz .Lhpb_784
	v_add_co_u32_e32 v24, vcc, 0x10b000, v20
	s_nop 1
	v_addc_co_u32_e32 v25, vcc, 0, v21, vcc
	v_add_co_u32_e32 v26, vcc, 0x109000, v20
	s_nop 1
	v_addc_co_u32_e32 v27, vcc, 0, v21, vcc
.Lhpb_784:
	v_mov_b32_e32 v204, 0
	s_and_b64 vcc, exec, s[38:39]
	v_mov_b32_e32 v206, 0
	v_mov_b32_e32 v207, 0
	v_mov_b32_e32 v178, 0
	v_mov_b32_e32 v179, 0
	s_cbranch_vccnz .Lhpb_786
	v_add_co_u32_e32 v24, vcc, 0x14d000, v20
	s_nop 1
	v_addc_co_u32_e32 v25, vcc, 0, v21, vcc
	v_add_co_u32_e32 v26, vcc, 0x14b000, v20
	s_nop 1
	v_addc_co_u32_e32 v27, vcc, 0, v21, vcc
.Lhpb_786:
	s_and_b64 vcc, exec, s[38:39]
	v_mov_b32_e32 v205, 0
	v_mov_b32_e32 v176, 0
	v_mov_b32_e32 v177, 0
	s_cbranch_vccnz .Lhpb_788
	v_add_co_u32_e32 v24, vcc, 0x18f000, v20
	s_nop 1
	v_addc_co_u32_e32 v25, vcc, 0, v21, vcc
	v_add_co_u32_e32 v26, vcc, 0x18d000, v20
	s_nop 1
	v_addc_co_u32_e32 v27, vcc, 0, v21, vcc
.Lhpb_788:
	s_and_b64 vcc, exec, s[38:39]
	s_cbranch_vccnz .Lhpb_791
	v_add_co_u32_e32 v24, vcc, 0x1d1000, v20
	s_nop 1
	v_addc_co_u32_e32 v25, vcc, 0, v21, vcc
	v_add_co_u32_e32 v20, vcc, 0x1cf000, v20
	s_nop 1
	v_addc_co_u32_e32 v21, vcc, 0, v21, vcc
	s_branch .Lhpb_792

; __device__ __forceinline__ void hg_passB(const Ptrs& P, int l, int b, int hd, int ch, unsigned char* lds, int tid, bool dost) {
;     ...
;     bf16x8 qf[8][4];
; #pragma unroll
;     for (int j = 0; j < 8; ++j)
; #pragma unroll
;         for (int ks = 0; ks < 4; ++ks) { qf[j][ks] = (bf16x8){0, 0, 0, 0, 0, 0, 0, 0}; if (j < nsub) qf[j][ks] = *(const bf16x8*)(PJ + (row0 + 16 * j + lc) * PW + C_HQ + hd * 128 + 32 * ks + 8 * g); }
.Lhpb_792:
	v_mad_u64_u32 v[20:21], s[4:5], v22, s34, 0
	v_lshl_add_u64 v[192:193], v[160:161], 0, v[20:21]
	v_lshlrev_b32_e32 v112, 1, v18
	v_mov_b32_e32 v113, v16
	v_lshl_add_u64 v[18:19], v[192:193], 0, s[96:97]
	v_lshl_add_u64 v[26:27], v[18:19], 0, v[112:113]
	s_mov_b64 s[4:5], 0x2a00
	v_add_co_u32_e32 v38, vcc, 0x2000, v26
	v_lshl_add_u64 v[28:29], v[26:27], 0, s[4:5]
	s_nop 0
	v_addc_co_u32_e32 v39, vcc, 0, v27, vcc
	s_nop 0
	s_mov_b64 s[4:5], 0x44a00
	s_and_b64 vcc, exec, s[38:39]
	v_lshl_add_u64 v[54:55], v[26:27], 0, s[4:5]
	s_cbranch_vccnz .Lhpb_797
	s_and_b64 vcc, exec, s[38:39]
	s_cbranch_vccnz .Lhpb_798
.Lhpb_794:
	s_and_b64 vcc, exec, s[38:39]
	s_cbranch_vccnz .Lhpb_799
.Lhpb_795:
	s_and_b64 vcc, exec, s[38:39]
	s_cbranch_vccnz .Lhpb_800
.Lhpb_796:
	s_branch .Lhpb_801
.Lhpb_797:
	v_mov_b32_e32 v26, 0
	v_mov_b32_e32 v27, v26
	v_mov_b32_e32 v28, v26
	v_mov_b32_e32 v29, v26
	s_and_b64 vcc, exec, s[38:39]
	s_cbranch_vccz .Lhpb_794

; __device__ __forceinline__ void hg_passB(const Ptrs& P, int l, int b, int hd, int ch, unsigned char* lds, int tid, bool dost) {
;     ...
;     bf16x8 qf[8][4];
; #pragma unroll
;     for (int j = 0; j < 8; ++j)
; #pragma unroll
;         for (int ks = 0; ks < 4; ++ks) { qf[j][ks] = (bf16x8){0, 0, 0, 0, 0, 0, 0, 0}; if (j < nsub) qf[j][ks] = *(const bf16x8*)(PJ + (row0 + 16 * j + lc) * PW + C_HQ + hd * 128 + 32 * ks + 8 * g); }
.Lhpb_801:
	v_lshl_add_u64 v[58:59], v[192:193], 0, s[96:97]
	v_mov_b32_e32 v113, v16
	v_lshl_add_u64 v[58:59], v[58:59], 0, v[112:113]
	s_mov_b64 s[4:5], 0x86a00
	s_and_b64 vcc, exec, s[38:39]
	v_lshl_add_u64 v[70:71], v[58:59], 0, s[4:5]
	s_cbranch_vccnz .Lhpb_806
	s_and_b64 vcc, exec, s[38:39]
	s_cbranch_vccnz .Lhpb_807
.Lhpb_803:
	s_and_b64 vcc, exec, s[38:39]
	s_cbranch_vccnz .Lhpb_808
.Lhpb_804:
	s_and_b64 vcc, exec, s[38:39]
	s_cbranch_vccnz .Lhpb_809
.Lhpb_805:
	s_branch .Lhpb_810
.Lhpb_806:
	v_mov_b32_e32 v58, 0
	v_mov_b32_e32 v59, v58
	v_mov_b32_e32 v60, v58
	v_mov_b32_e32 v61, v58
	s_and_b64 vcc, exec, s[38:39]
	s_cbranch_vccz .Lhpb_803

; __device__ __forceinline__ void hg_passB(const Ptrs& P, int l, int b, int hd, int ch, unsigned char* lds, int tid, bool dost) {
;     ...
;     bf16x8 qf[8][4];
; #pragma unroll
;     for (int j = 0; j < 8; ++j)
; #pragma unroll
;         for (int ks = 0; ks < 4; ++ks) { qf[j][ks] = (bf16x8){0, 0, 0, 0, 0, 0, 0, 0}; if (j < nsub) qf[j][ks] = *(const bf16x8*)(PJ + (row0 + 16 * j + lc) * PW + C_HQ + hd * 128 + 32 * ks + 8 * g); }
.Lhpb_810:
	v_lshl_add_u64 v[74:75], v[192:193], 0, s[96:97]
	v_mov_b32_e32 v113, v16
	v_lshl_add_u64 v[74:75], v[74:75], 0, v[112:113]
	s_mov_b64 s[4:5], 0xc8a00
	s_and_b64 vcc, exec, s[38:39]
	v_lshl_add_u64 v[86:87], v[74:75], 0, s[4:5]
	s_cbranch_vccnz .Lhpb_815
	s_and_b64 vcc, exec, s[38:39]
	s_cbranch_vccnz .Lhpb_816
.Lhpb_812:
	s_and_b64 vcc, exec, s[38:39]
	s_cbranch_vccnz .Lhpb_817
.Lhpb_813:
	s_and_b64 vcc, exec, s[38:39]
	s_cbranch_vccnz .Lhpb_818
.Lhpb_814:
	s_branch .Lhpb_819
.Lhpb_815:
	v_mov_b32_e32 v74, 0
	v_mov_b32_e32 v75, v74
	v_mov_b32_e32 v76, v74
	v_mov_b32_e32 v77, v74
	s_and_b64 vcc, exec, s[38:39]
	s_cbranch_vccz .Lhpb_812

; __device__ __forceinline__ void hg_passB(const Ptrs& P, int l, int b, int hd, int ch, unsigned char* lds, int tid, bool dost) {
;     ...
;     bf16x8 qf[8][4];
; #pragma unroll
;     for (int j = 0; j < 8; ++j)
; #pragma unroll
;         for (int ks = 0; ks < 4; ++ks) { qf[j][ks] = (bf16x8){0, 0, 0, 0, 0, 0, 0, 0}; if (j < nsub) qf[j][ks] = *(const bf16x8*)(PJ + (row0 + 16 * j + lc) * PW + C_HQ + hd * 128 + 32 * ks + 8 * g); }
.Lhpb_819:
	v_lshl_add_u64 v[90:91], v[192:193], 0, s[96:97]
	v_mov_b32_e32 v113, v16
	v_lshl_add_u64 v[90:91], v[90:91], 0, v[112:113]
	s_mov_b64 s[4:5], 0x10aa00
	s_and_b64 vcc, exec, s[38:39]
	v_lshl_add_u64 v[102:103], v[90:91], 0, s[4:5]
	s_cbranch_vccnz .Lhpb_824
	s_and_b64 vcc, exec, s[38:39]
	s_cbranch_vccnz .Lhpb_825
.Lhpb_821:
	s_and_b64 vcc, exec, s[38:39]
	s_cbranch_vccnz .Lhpb_826
.Lhpb_822:
	s_and_b64 vcc, exec, s[38:39]
	s_cbranch_vccnz .Lhpb_827
.Lhpb_823:
	s_branch .Lhpb_828
.Lhpb_824:
	v_mov_b32_e32 v90, 0
	v_mov_b32_e32 v91, v90
	v_mov_b32_e32 v92, v90
	v_mov_b32_e32 v93, v90
	s_and_b64 vcc, exec, s[38:39]
	s_cbranch_vccz .Lhpb_821

; __device__ __forceinline__ void hg_passB(const Ptrs& P, int l, int b, int hd, int ch, unsigned char* lds, int tid, bool dost) {
;     ...
;     bf16x8 qf[8][4];
; #pragma unroll
;     for (int j = 0; j < 8; ++j)
; #pragma unroll
;         for (int ks = 0; ks < 4; ++ks) { qf[j][ks] = (bf16x8){0, 0, 0, 0, 0, 0, 0, 0}; if (j < nsub) qf[j][ks] = *(const bf16x8*)(PJ + (row0 + 16 * j + lc) * PW + C_HQ + hd * 128 + 32 * ks + 8 * g); }
.Lhpb_828:
	v_lshl_add_u64 v[106:107], v[192:193], 0, s[96:97]
	v_mov_b32_e32 v113, v16
	v_lshl_add_u64 v[106:107], v[106:107], 0, v[112:113]
	s_mov_b64 s[4:5], 0x14ca00
	s_and_b64 vcc, exec, s[38:39]
	v_lshl_add_u64 v[122:123], v[106:107], 0, s[4:5]
	s_cbranch_vccnz .Lhpb_833
	s_and_b64 vcc, exec, s[38:39]
	s_cbranch_vccnz .Lhpb_834
.Lhpb_830:
	s_and_b64 vcc, exec, s[38:39]
	s_cbranch_vccnz .Lhpb_835
.Lhpb_831:
	s_and_b64 vcc, exec, s[38:39]
	s_cbranch_vccnz .Lhpb_836
.Lhpb_832:
	s_branch .Lhpb_837
.Lhpb_833:
	v_mov_b32_e32 v106, 0
	v_mov_b32_e32 v107, v106
	v_mov_b32_e32 v108, v106
	v_mov_b32_e32 v109, v106
	s_and_b64 vcc, exec, s[38:39]
	s_cbranch_vccz .Lhpb_830

; __device__ __forceinline__ void hg_passB(const Ptrs& P, int l, int b, int hd, int ch, unsigned char* lds, int tid, bool dost) {
;     ...
;     bf16x8 qf[8][4];
; #pragma unroll
;     for (int j = 0; j < 8; ++j)
; #pragma unroll
;         for (int ks = 0; ks < 4; ++ks) { qf[j][ks] = (bf16x8){0, 0, 0, 0, 0, 0, 0, 0}; if (j < nsub) qf[j][ks] = *(const bf16x8*)(PJ + (row0 + 16 * j + lc) * PW + C_HQ + hd * 128 + 32 * ks + 8 * g); }
.Lhpb_837:
	v_lshl_add_u64 v[126:127], v[192:193], 0, s[96:97]
	v_mov_b32_e32 v113, v16
	v_lshl_add_u64 v[126:127], v[126:127], 0, v[112:113]
	s_mov_b64 s[4:5], 0x18ea00
	s_and_b64 vcc, exec, s[38:39]
	v_lshl_add_u64 v[138:139], v[126:127], 0, s[4:5]
	s_cbranch_vccnz .Lhpb_842
	s_and_b64 vcc, exec, s[38:39]
	s_cbranch_vccnz .Lhpb_843
.Lhpb_839:
	s_and_b64 vcc, exec, s[38:39]
	s_cbranch_vccnz .Lhpb_844
.Lhpb_840:
	s_and_b64 vcc, exec, s[38:39]
	s_cbranch_vccnz .Lhpb_845
.Lhpb_841:
	s_branch .Lhpb_846
.Lhpb_842:
	v_mov_b32_e32 v126, 0
	v_mov_b32_e32 v127, v126
	v_mov_b32_e32 v128, v126
	v_mov_b32_e32 v129, v126
	s_and_b64 vcc, exec, s[38:39]
	s_cbranch_vccz .Lhpb_839

; __device__ __forceinline__ void hg_passB(const Ptrs& P, int l, int b, int hd, int ch, unsigned char* lds, int tid, bool dost) {
;     ...
;     bf16x8 qf[8][4];
; #pragma unroll
;     for (int j = 0; j < 8; ++j)
; #pragma unroll
;         for (int ks = 0; ks < 4; ++ks) { qf[j][ks] = (bf16x8){0, 0, 0, 0, 0, 0, 0, 0}; if (j < nsub) qf[j][ks] = *(const bf16x8*)(PJ + (row0 + 16 * j + lc) * PW + C_HQ + hd * 128 + 32 * ks + 8 * g); }
.Lhpb_846:
	v_lshl_add_u64 v[142:143], v[192:193], 0, s[96:97]
	v_mov_b32_e32 v113, v16
	v_lshl_add_u64 v[112:113], v[142:143], 0, v[112:113]
	s_mov_b64 s[4:5], 0x1d0a00
	s_and_b64 vcc, exec, s[38:39]
	v_lshl_add_u64 v[112:113], v[112:113], 0, s[4:5]
	s_cbranch_vccnz .Lhpb_851
	s_and_b64 vcc, exec, s[38:39]
	s_cbranch_vccnz .Lhpb_852
.Lhpb_848:
	s_and_b64 vcc, exec, s[38:39]
	s_cbranch_vccnz .Lhpb_853
.Lhpb_849:
	s_and_b64 vcc, exec, s[38:39]
	s_cbranch_vccnz .Lhpb_854
.Lhpb_850:
	s_branch .Lhpb_stage
.Lhpb_851:
	v_mov_b32_e32 v142, 0
	v_mov_b32_e32 v143, v142
	v_mov_b32_e32 v144, v142
	v_mov_b32_e32 v145, v142
	s_and_b64 vcc, exec, s[38:39]
	s_cbranch_vccz .Lhpb_848

; __device__ __forceinline__ void hg_passB(const Ptrs& P, int l, int b, int hd, int ch, unsigned char* lds, int tid, bool dost) {
;     ...
;     bf16x8 sfr[4];
; #pragma unroll
;     for (int ks = 0; ks < 4; ++ks) sfr[ks] = *(const bf16x8*)(HS + (16 * w + lc) * 128 + 32 * ks + 8 * g);
;     u32x2 ol[8], gv_[8];
; #pragma unroll
;     for (int j = 0; j < 8; ++j) { ol[j] = (u32x2){0u, 0u}; gv_[j] = ol[j];
;         if (j < nsub) { const bf16_t* rp = PJ + (row0 + 16 * j + lc) * PW + hd * 128 + 16 * w + 4 * g; ol[j] = *(const u32x2*)(rp + C_HI); gv_[j] = *(const u32x2*)(rp + C_HG); } }
;     bf16x8 qf[8][4];
; #pragma unroll
;     for (int j = 0; j < 8; ++j)
; #pragma unroll
;         for (int ks = 0; ks < 4; ++ks) { qf[j][ks] = (bf16x8){0, 0, 0, 0, 0, 0, 0, 0}; if (j < nsub) qf[j][ks] = *(const bf16x8*)(PJ + (row0 + 16 * j + lc) * PW + C_HQ + hd * 128 + 32 * ks + 8 * g); }
.Lhpb_stage:
	v_lshrrev_b32_e32 v228, 6, v211
	v_bfe_u32 v229, v211, 4, 2
	v_and_b32_e32 v230, 15, v211
	v_lshl_add_u32 v231, v228, 2, v229
	v_and_b32_e32 v226, 15, v231
	v_xor_b32_e32 v226, v226, v230
	v_lshlrev_b32_e32 v226, 4, v226
	v_mov_b32_e32 v227, 0
	v_add_u32_e32 v231, s15, v231
	v_mad_u64_u32 v[218:219], vcc, v231, s34, v[160:161]
	v_lshl_add_u64 v[218:219], v[218:219], 0, s[96:97]
	v_lshl_add_u64 v[218:219], v[218:219], 0, v[226:227]
	s_mov_b64 s[100:101], 0x2a00
	v_lshl_add_u64 v[220:221], v[218:219], 0, s[100:101]
	s_mov_b64 s[100:101], 0x3a00
	v_lshl_add_u64 v[222:223], v[218:219], 0, s[100:101]
	s_mov_b64 s[100:101], 0x1000
	v_lshl_add_u64 v[224:225], v[218:219], 0, s[100:101]
	s_mov_b64 s[100:101], 0x84000
	v_readfirstlane_b32 s17, v228
	s_nop 3
	s_lshl_b32 s17, s17, 10
	s_add_i32 m0, s17, 0x0
	s_nop 0
	global_load_lds_dwordx4 v[220:221], off
	s_add_i32 m0, s17, 0x8000
	s_nop 0
	global_load_lds_dwordx4 v[222:223], off
	s_add_i32 m0, s17, 0x10000
	s_nop 0
	global_load_lds_dwordx4 v[224:225], off
	v_lshl_add_u64 v[220:221], v[220:221], 0, s[100:101]
	v_lshl_add_u64 v[222:223], v[222:223], 0, s[100:101]
	v_lshl_add_u64 v[224:225], v[224:225], 0, s[100:101]
	s_add_i32 m0, s17, 0x2000
	s_nop 0
	global_load_lds_dwordx4 v[220:221], off
	s_add_i32 m0, s17, 0xa000
	s_nop 0
	global_load_lds_dwordx4 v[222:223], off
	s_add_i32 m0, s17, 0x12000
	s_nop 0
	global_load_lds_dwordx4 v[224:225], off
	v_lshl_add_u64 v[220:221], v[220:221], 0, s[100:101]
	v_lshl_add_u64 v[222:223], v[222:223], 0, s[100:101]
	v_lshl_add_u64 v[224:225], v[224:225], 0, s[100:101]
	s_add_i32 m0, s17, 0x4000
	s_nop 0
	global_load_lds_dwordx4 v[220:221], off
	s_add_i32 m0, s17, 0xc000
	s_nop 0
	global_load_lds_dwordx4 v[222:223], off
	s_add_i32 m0, s17, 0x14000
	s_nop 0
	global_load_lds_dwordx4 v[224:225], off
	v_lshl_add_u64 v[220:221], v[220:221], 0, s[100:101]
	v_lshl_add_u64 v[222:223], v[222:223], 0, s[100:101]
	v_lshl_add_u64 v[224:225], v[224:225], 0, s[100:101]
	s_add_i32 m0, s17, 0x6000
	s_nop 0
	global_load_lds_dwordx4 v[220:221], off
	s_add_i32 m0, s17, 0xe000
	s_nop 0
	global_load_lds_dwordx4 v[222:223], off
	s_add_i32 m0, s17, 0x16000
	s_nop 0
	global_load_lds_dwordx4 v[224:225], off
	v_and_b32_e32 v232, 3, v230
	v_xor_b32_e32 v232, v232, v229
	v_lshrrev_b32_e32 v233, 2, v230
	v_xor_b32_e32 v244, 0, v233
	v_lshl_or_b32 v244, v244, 2, v232
	v_lshlrev_b32_e32 v244, 4, v244
	v_lshl_add_u32 v244, v230, 8, v244
	v_xor_b32_e32 v245, 1, v233
	v_lshl_or_b32 v245, v245, 2, v232
	v_lshlrev_b32_e32 v245, 4, v245
	v_lshl_add_u32 v245, v230, 8, v245
	v_xor_b32_e32 v246, 2, v233
	v_lshl_or_b32 v246, v246, 2, v232
	v_lshlrev_b32_e32 v246, 4, v246
	v_lshl_add_u32 v246, v230, 8, v246
	v_xor_b32_e32 v247, 3, v233
	v_lshl_or_b32 v247, v247, 2, v232
	v_lshlrev_b32_e32 v247, 4, v247
	v_lshl_add_u32 v247, v230, 8, v247
	v_lshrrev_b32_e32 v250, 1, v229
	v_lshl_add_u32 v250, v228, 1, v250
	v_xor_b32_e32 v250, v250, v230
	v_lshlrev_b32_e32 v250, 4, v250
	v_and_b32_e32 v248, 1, v229
	v_lshl_add_u32 v250, v248, 3, v250
	v_lshl_add_u32 v250, v230, 8, v250
	v_add_u32_e32 v248, 0x8000, v250
	v_add_u32_e32 v249, 0x10000, v250
	s_waitcnt vmcnt(0)
	s_barrier
	ds_read_b128 v[42:45], v244
	ds_read_b128 v[18:21], v245
	ds_read_b128 v[22:25], v246
	ds_read_b128 v[38:41], v247
	ds_read_b64 v[110:111], v248
	ds_read_b64 v[190:191], v249
	ds_read_b128 v[26:29], v244 offset:4096
	ds_read_b128 v[46:49], v245 offset:4096
	ds_read_b128 v[50:53], v246 offset:4096
	ds_read_b128 v[54:57], v247 offset:4096
	ds_read_b64 v[198:199], v248 offset:4096
	ds_read_b64 v[186:187], v249 offset:4096
	ds_read_b128 v[58:61], v244 offset:8192
	ds_read_b128 v[62:65], v245 offset:8192
	ds_read_b128 v[66:69], v246 offset:8192
	ds_read_b128 v[70:73], v247 offset:8192
	ds_read_b64 v[196:197], v248 offset:8192
	ds_read_b64 v[184:185], v249 offset:8192
	ds_read_b128 v[74:77], v244 offset:12288
	ds_read_b128 v[78:81], v245 offset:12288
	ds_read_b128 v[82:85], v246 offset:12288
	ds_read_b128 v[86:89], v247 offset:12288
	ds_read_b64 v[202:203], v248 offset:12288
	ds_read_b64 v[182:183], v249 offset:12288
	ds_read_b128 v[90:93], v244 offset:16384
	ds_read_b128 v[94:97], v245 offset:16384
	ds_read_b128 v[98:101], v246 offset:16384
	ds_read_b128 v[102:105], v247 offset:16384
	ds_read_b64 v[200:201], v248 offset:16384
	ds_read_b64 v[180:181], v249 offset:16384
	ds_read_b128 v[106:109], v244 offset:20480
	ds_read_b128 v[114:117], v245 offset:20480
	ds_read_b128 v[118:121], v246 offset:20480
	ds_read_b128 v[122:125], v247 offset:20480
	ds_read_b64 v[206:207], v248 offset:20480
	ds_read_b64 v[178:179], v249 offset:20480
	ds_read_b128 v[126:129], v244 offset:24576
	ds_read_b128 v[130:133], v245 offset:24576
	ds_read_b128 v[134:137], v246 offset:24576
	ds_read_b128 v[138:141], v247 offset:24576
	ds_read_b64 v[204:205], v248 offset:24576
	ds_read_b64 v[176:177], v249 offset:24576
	ds_read_b128 v[142:145], v244 offset:28672
	ds_read_b128 v[146:149], v245 offset:28672
	ds_read_b128 v[150:153], v246 offset:28672
	ds_read_b128 v[154:157], v247 offset:28672
	ds_read_b64 v[208:209], v248 offset:28672
	ds_read_b64 v[174:175], v249 offset:28672
	s_waitcnt lgkmcnt(0)
	s_branch .LBB0_855
